# dense attention loop: remove three vmcnt waits already satisfied by the explicit vmcnt(4) before the first K/V LDS write
# speedup vs baseline: 1.0160x; 1.0106x over previous
; __device__ __forceinline__ void finishSM(f32x16& p0, f32x16& p1, float alpha, float& l_reg, bf16x8& pa0, bf16x8& pa1, bf16x8& pa2, bf16x8& pa3) {
; #pragma unroll
;     for (int r = 0; r < 16; ++r) p1[r] = __builtin_amdgcn_exp2f(p1[r]);
;     float ps = 0;
; #pragma unroll
;     for (int r = 0; r < 16; ++r) ps += p0[r];
; #pragma unroll
;     for (int r = 0; r < 16; ++r) ps += p1[r];
;     { auto rr = __builtin_amdgcn_permlane32_swap(__float_as_uint(ps), __float_as_uint(ps), false, false);
;       ps = __uint_as_float(rr[0]) + __uint_as_float(rr[1]); }
;     l_reg = l_reg * alpha + ps;
;     PK4(p0, 0, pa0); PK4(p0, 8, pa1); PK4(p1, 0, pa2); PK4(p1, 8, pa3);
; }
; __device__ __forceinline__ void qkt(f32x16& p0, f32x16& p1, const bf16_t* Ks, const bf16x8* qr, int r32, int hi) {
;     p0 = f32x16{}; p1 = f32x16{};
; #pragma unroll
;     for (int d0 = 0; d0 < 8; ++d0) { const int cb = (d0 * 16 + hi * 8) * 2;
;         bf16x8 b0 = *reinterpret_cast<const bf16x8*>((const char*)Ks + KSWZ(r32, cb));
;         bf16x8 b1 = *reinterpret_cast<const bf16x8*>((const char*)Ks + KSWZ(32 + r32, cb));
;         p0 = __builtin_amdgcn_mfma_f32_32x32x16_bf16(b0, qr[d0], p0, 0, 0, 0);
;         p1 = __builtin_amdgcn_mfma_f32_32x32x16_bf16(b1, qr[d0], p1, 0, 0, 0); }
; }
.LBB0_530:
	ds_read_b128 v[64:67], v200 offset:49152
	ds_read_b128 v[68:71], v200 offset:57344
	ds_read_b128 v[216:219], v205 offset:49152
	ds_read_b128 v[220:223], v205 offset:57344
	v_add_f32_e32 v160, 0, v161
	v_add_f32_e32 v160, v175, v160
	s_waitcnt lgkmcnt(3)
	v_mfma_f32_32x32x16_bf16 v[80:95], v[64:67], v[124:127], 0
	v_add_f32_e32 v160, v162, v160
	v_add_f32_e32 v160, v212, v160
	v_add_f32_e32 v160, v174, v160
	v_add_f32_e32 v160, v215, v160
	v_add_f32_e32 v160, v163, v160
	v_add_f32_e32 v160, v173, v160
	v_add_f32_e32 v160, v169, v160
	s_waitcnt lgkmcnt(2)
	v_mfma_f32_32x32x16_bf16 v[64:79], v[68:71], v[124:127], 0
	v_add_f32_e32 v160, v171, v160
	v_add_f32_e32 v160, v170, v160
	v_add_f32_e32 v160, v172, v160
	v_exp_f32_e32 v158, v158
	v_add_f32_e32 v160, v165, v160
	v_exp_f32_e32 v159, v159
	v_add_f32_e32 v160, v167, v160
	s_waitcnt lgkmcnt(1)
	v_mfma_f32_32x32x16_bf16 v[80:95], v[216:219], v[120:123], v[80:95]
	v_exp_f32_e32 v156, v156
	v_add_f32_e32 v160, v166, v160
	v_exp_f32_e32 v157, v157
	v_add_f32_e32 v160, v168, v160
	v_exp_f32_e32 v152, v152
	v_add_f32_e32 v160, v158, v160
	v_exp_f32_e32 v153, v153
	s_waitcnt lgkmcnt(0)
	v_mfma_f32_32x32x16_bf16 v[64:79], v[220:223], v[120:123], v[64:79]
	ds_read_b128 v[216:219], v204 offset:49152
	ds_read_b128 v[220:223], v204 offset:57344
	v_add_f32_e32 v160, v159, v160
	v_exp_f32_e32 v148, v148
	v_add_f32_e32 v160, v156, v160
	v_exp_f32_e32 v149, v149
	v_add_f32_e32 v160, v157, v160
	v_exp_f32_e32 v146, v146
	s_waitcnt lgkmcnt(1)
	v_mfma_f32_32x32x16_bf16 v[80:95], v[216:219], v[116:119], v[80:95]
	v_add_f32_e32 v160, v152, v160
	v_exp_f32_e32 v147, v147
	v_add_f32_e32 v160, v153, v160
	v_exp_f32_e32 v154, v154
	v_add_f32_e32 v160, v148, v160
	v_exp_f32_e32 v155, v155
	v_add_f32_e32 v160, v149, v160
	s_waitcnt lgkmcnt(0)
	v_mfma_f32_32x32x16_bf16 v[64:79], v[220:223], v[116:119], v[64:79]
	ds_read_b128 v[216:219], v201 offset:49152
	ds_read_b128 v[220:223], v201 offset:57344
	v_exp_f32_e32 v150, v150
	v_add_f32_e32 v160, v146, v160
	v_exp_f32_e32 v151, v151
	v_add_f32_e32 v160, v147, v160
	v_exp_f32_e32 v144, v144
	v_add_f32_e32 v160, v154, v160
	s_waitcnt lgkmcnt(1)
	v_mfma_f32_32x32x16_bf16 v[80:95], v[216:219], v[112:115], v[80:95]
	v_exp_f32_e32 v145, v145
	v_add_f32_e32 v160, v155, v160
	v_add_f32_e32 v160, v150, v160
	v_add_f32_e32 v160, v151, v160
	v_add_f32_e32 v160, v144, v160
	v_add_f32_e32 v209, v145, v160
	v_mov_b32_e32 v210, v209
	s_waitcnt lgkmcnt(0)
	v_mfma_f32_32x32x16_bf16 v[64:79], v[220:223], v[112:115], v[64:79]
	ds_read_b128 v[216:219], v202 offset:49152
	ds_read_b128 v[220:223], v202 offset:57344
	v_permlane32_swap_b32_e32 v209, v210
	s_waitcnt lgkmcnt(1)
	v_mfma_f32_32x32x16_bf16 v[80:95], v[216:219], v[108:111], v[80:95]
	s_waitcnt lgkmcnt(0)
	v_mfma_f32_32x32x16_bf16 v[64:79], v[220:223], v[108:111], v[64:79]
	ds_read_b128 v[216:219], v203 offset:49152
	ds_read_b128 v[220:223], v203 offset:57344
	s_waitcnt lgkmcnt(1)
	v_mfma_f32_32x32x16_bf16 v[80:95], v[216:219], v[104:107], v[80:95]
	s_waitcnt lgkmcnt(0)
	v_mfma_f32_32x32x16_bf16 v[64:79], v[220:223], v[104:107], v[64:79]
	ds_read_b128 v[216:219], v206 offset:49152
	ds_read_b128 v[220:223], v206 offset:57344
	s_waitcnt lgkmcnt(1)
	v_mfma_f32_32x32x16_bf16 v[80:95], v[216:219], v[100:103], v[80:95]
	s_waitcnt lgkmcnt(0)
	v_mfma_f32_32x32x16_bf16 v[64:79], v[220:223], v[100:103], v[64:79]
	ds_read_b128 v[216:219], v207 offset:49152
	ds_read_b128 v[220:223], v207 offset:57344
	v_cvt_pk_bf16_f32 v160, v161, v175
	v_cvt_pk_bf16_f32 v161, v162, v212
	v_cvt_pk_bf16_f32 v162, v174, v215
	v_cvt_pk_bf16_f32 v163, v163, v173
	v_cvt_pk_bf16_f32 v212, v169, v171
	v_cvt_pk_bf16_f32 v213, v170, v172
	s_waitcnt lgkmcnt(1)
	v_mfma_f32_32x32x16_bf16 v[80:95], v[216:219], v[96:99], v[80:95]
	v_permlane32_swap_b32_e32 v160, v162
	v_cvt_pk_bf16_f32 v214, v165, v167
	v_cvt_pk_bf16_f32 v215, v166, v168
	v_cvt_pk_bf16_f32 v166, v158, v159
	v_cvt_pk_bf16_f32 v167, v156, v157
	v_cvt_pk_bf16_f32 v168, v152, v153
	s_waitcnt lgkmcnt(0)
	v_mfma_f32_32x32x16_bf16 v[64:79], v[220:223], v[96:99], v[64:79]
	v_cvt_pk_bf16_f32 v169, v148, v149
	v_cvt_pk_bf16_f32 v170, v146, v147
	v_cvt_pk_bf16_f32 v171, v154, v155
	v_cvt_pk_bf16_f32 v172, v150, v151
	v_cvt_pk_bf16_f32 v173, v144, v145
	v_permlane32_swap_b32_e32 v161, v163
	v_permlane32_swap_b32_e32 v212, v214
	v_permlane32_swap_b32_e32 v213, v215
	v_permlane32_swap_b32_e32 v166, v168
	v_permlane32_swap_b32_e32 v167, v169
	v_permlane32_swap_b32_e32 v170, v172
	v_permlane32_swap_b32_e32 v171, v173
	s_mov_b32 s4, 0xfff28000
	v_add_co_u32_e32 v148, vcc, s4, v186
	s_mov_b32 s4, 0xfff70000
	s_nop 0
	v_addc_co_u32_e32 v149, vcc, -1, v187, vcc
	v_add_co_u32_e32 v152, vcc, s4, v186
	s_nop 1
	v_addc_co_u32_e32 v153, vcc, -1, v187, vcc
	global_load_dwordx4 v[144:147], v[148:149], off
	s_nop 0
	global_load_dwordx4 v[148:151], v[148:149], off offset:-512
	s_nop 0
	global_load_dwordx4 v[156:159], v[152:153], off
	s_nop 0
	global_load_dwordx4 v[152:155], v[152:153], off offset:-512
	ds_read_b64_tr_b16 v[216:217], v195 offset:0
	ds_read_b64_tr_b16 v[218:219], v195 offset:0x800
	ds_read_b64_tr_b16 v[220:221], v195 offset:0x1000
	ds_read_b64_tr_b16 v[222:223], v195 offset:0x1800
	ds_read_b64_tr_b16 v[224:225], v195 offset:0x2000
	ds_read_b64_tr_b16 v[226:227], v195 offset:0x2800
	ds_read_b64_tr_b16 v[228:229], v195 offset:0x3000
	ds_read_b64_tr_b16 v[230:231], v195 offset:0x3800
	s_waitcnt lgkmcnt(0)
; #define SBAR() __builtin_amdgcn_sched_barrier(0)
; __device__ __forceinline__ void partialSM(f32x16& p0, f32x16& p1, float& m_reg, float& mn, float& alpha) {
;     constexpr float C = SCALE * LOG2E;
;     float pmax = p0[0];
; #pragma unroll
;     for (int r = 1; r < 16; ++r) pmax = fmaxf(pmax, p0[r]);
; #pragma unroll
;     for (int r = 0; r < 16; ++r) pmax = fmaxf(pmax, p1[r]);
;     { auto rr = __builtin_amdgcn_permlane32_swap(__float_as_uint(pmax), __float_as_uint(pmax), false, false);
;       pmax = fmaxf(__uint_as_float(rr[0]), __uint_as_float(rr[1])); }
;     if (__builtin_expect(__all(pmax - m_reg <= THR / SCALE), 1)) { mn = m_reg; alpha = 1.f; }
;     else { mn = fmaxf(m_reg, pmax); alpha = __builtin_amdgcn_exp2f((m_reg - mn) * C); m_reg = mn; }
; template <int D0> __device__ __forceinline__ void pv_one(f32x16& od, int vb, bf16x8 pa0, bf16x8 pa1, bf16x8 pa2, bf16x8 pa3) {
;     const s16x4 l0 = tr_read<v_rd_off(D0, 0, 0)>(vb), h0 = tr_read<v_rd_off(D0, 0, 1)>(vb), l1 = tr_read<v_rd_off(D0, 1, 0)>(vb), h1 = tr_read<v_rd_off(D0, 1, 1)>(vb);
;     const s16x4 l2 = tr_read<v_rd_off(D0, 2, 0)>(vb), h2 = tr_read<v_rd_off(D0, 2, 1)>(vb), l3 = tr_read<v_rd_off(D0, 3, 0)>(vb), h3 = tr_read<v_rd_off(D0, 3, 1)>(vb);
;     asm volatile("s_waitcnt lgkmcnt(0)" ::: "memory"); SBAR();
;     ...
;     od = __builtin_amdgcn_mfma_f32_32x32x16_bf16(pa0, PKV(l0, h0), od, 0, 0, 0);
;     od = __builtin_amdgcn_mfma_f32_32x32x16_bf16(pa1, PKV(l1, h1), od, 0, 0, 0);
;     od = __builtin_amdgcn_mfma_f32_32x32x16_bf16(pa2, PKV(l2, h2), od, 0, 0, 0);
;     od = __builtin_amdgcn_mfma_f32_32x32x16_bf16(pa3, PKV(l3, h3), od, 0, 0, 0);
;     ...
; }
; __device__ __forceinline__ void pv_d0(f32x16* o, int vb, bf16x8 pa0, bf16x8 pa1, bf16x8 pa2, bf16x8 pa3) {
;     pv_one<0>(o[0], vb, pa0, pa1, pa2, pa3); pv_one<1>(o[1], vb, pa0, pa1, pa2, pa3); pv_one<2>(o[2], vb, pa0, pa1, pa2, pa3); pv_one<3>(o[3], vb, pa0, pa1, pa2, pa3);
	s_nop 0
	v_mfma_f32_32x32x16_bf16 v[48:63], v[160:163], v[216:219], v[48:63]
	ds_read_b64_tr_b16 v[216:217], v195 offset:0x200
	ds_read_b64_tr_b16 v[218:219], v195 offset:0xa00
	v_mfma_f32_32x32x16_bf16 v[48:63], v[212:215], v[220:223], v[48:63]
	ds_read_b64_tr_b16 v[220:221], v195 offset:0x1200
	ds_read_b64_tr_b16 v[222:223], v195 offset:0x1a00
	v_mfma_f32_32x32x16_bf16 v[48:63], v[166:169], v[224:227], v[48:63]
	ds_read_b64_tr_b16 v[224:225], v195 offset:0x2200
	ds_read_b64_tr_b16 v[226:227], v195 offset:0x2a00
	v_mfma_f32_32x32x16_bf16 v[48:63], v[170:173], v[228:231], v[48:63]
	ds_read_b64_tr_b16 v[228:229], v195 offset:0x3200
	ds_read_b64_tr_b16 v[230:231], v195 offset:0x3a00
	s_waitcnt lgkmcnt(0)
	v_mfma_f32_32x32x16_bf16 v[32:47], v[160:163], v[216:219], v[32:47]
	ds_read_b64_tr_b16 v[216:217], v195 offset:0x400
	ds_read_b64_tr_b16 v[218:219], v195 offset:0xc00
	v_mfma_f32_32x32x16_bf16 v[32:47], v[212:215], v[220:223], v[32:47]
	ds_read_b64_tr_b16 v[220:221], v195 offset:0x1400
	ds_read_b64_tr_b16 v[222:223], v195 offset:0x1c00
	v_mfma_f32_32x32x16_bf16 v[32:47], v[166:169], v[224:227], v[32:47]
	ds_read_b64_tr_b16 v[224:225], v195 offset:0x2400
	ds_read_b64_tr_b16 v[226:227], v195 offset:0x2c00
	v_mfma_f32_32x32x16_bf16 v[32:47], v[170:173], v[228:231], v[32:47]
	ds_read_b64_tr_b16 v[228:229], v195 offset:0x3400
	ds_read_b64_tr_b16 v[230:231], v195 offset:0x3c00
	s_waitcnt lgkmcnt(0)
	v_mfma_f32_32x32x16_bf16 v[16:31], v[160:163], v[216:219], v[16:31]
	ds_read_b64_tr_b16 v[216:217], v195 offset:0x600
	ds_read_b64_tr_b16 v[218:219], v195 offset:0xe00
	v_mfma_f32_32x32x16_bf16 v[16:31], v[212:215], v[220:223], v[16:31]
	ds_read_b64_tr_b16 v[220:221], v195 offset:0x1600
	ds_read_b64_tr_b16 v[222:223], v195 offset:0x1e00
	v_mfma_f32_32x32x16_bf16 v[16:31], v[166:169], v[224:227], v[16:31]
	ds_read_b64_tr_b16 v[224:225], v195 offset:0x2600
	ds_read_b64_tr_b16 v[226:227], v195 offset:0x2e00
	v_mfma_f32_32x32x16_bf16 v[16:31], v[170:173], v[228:231], v[16:31]
	ds_read_b64_tr_b16 v[228:229], v195 offset:0x3600
	ds_read_b64_tr_b16 v[230:231], v195 offset:0x3e00
	s_waitcnt lgkmcnt(0)
	v_mfma_f32_32x32x16_bf16 v[0:15], v[160:163], v[216:219], v[0:15]
	v_max_f32_e32 v160, v81, v81
	v_max_f32_e32 v161, v80, v80
	v_max_f32_e32 v160, v161, v160
	v_max3_f32 v160, v160, v82, v83
	v_max3_f32 v160, v160, v84, v85
	v_max3_f32 v160, v160, v86, v87
	v_max3_f32 v160, v160, v88, v89
	v_max3_f32 v160, v160, v90, v91
	v_max3_f32 v160, v160, v92, v93
	v_mfma_f32_32x32x16_bf16 v[0:15], v[212:215], v[220:223], v[0:15]
	v_max3_f32 v160, v160, v94, v95
	v_max3_f32 v160, v160, v64, v65
	v_max3_f32 v160, v160, v66, v67
	v_max3_f32 v160, v160, v68, v69
	v_max3_f32 v160, v160, v70, v71
	v_max3_f32 v160, v160, v72, v73
	v_max3_f32 v160, v160, v74, v75
	v_max3_f32 v160, v160, v76, v77
	v_mfma_f32_32x32x16_bf16 v[0:15], v[166:169], v[224:227], v[0:15]
	v_max3_f32 v160, v160, v78, v79
	v_mov_b32_e32 v161, v160
	s_nop 1
	v_permlane32_swap_b32_e32 v160, v161
	v_max_f32_e32 v161, v161, v161
	v_max_f32_e32 v160, v160, v160
	v_max_f32_e32 v160, v160, v161
	v_sub_f32_e32 v161, v160, v164
	v_cmp_ge_f32_e32 vcc, s70, v161
	v_max_f32_e32 v161, v164, v164
	v_max_f32_e32 v160, v161, v160
	v_mfma_f32_32x32x16_bf16 v[0:15], v[170:173], v[228:231], v[0:15]
	v_sub_f32_e32 v161, v164, v160
	v_mul_f32_e32 v161, 0x3e0293ee, v161
	v_exp_f32_e32 v161, v161
	s_cmp_eq_u64 vcc, exec
	s_cselect_b64 s[4:5], -1, 0
	s_barrier
	s_waitcnt vmcnt(4)
	v_cndmask_b32_e64 v211, v161, 1.0, s[4:5]
	v_cmp_gt_f32_e32 vcc, 1.0, v211
	ds_write_b128 v198, v[128:131]
	ds_write_b128 v199, v[136:139]
	ds_write_b128 v196, v[132:135] offset:32768
	ds_write_b128 v197, v[140:143] offset:32768
	s_cbranch_vccz .LBB0_534
	s_and_saveexec_b64 s[12:13], s[0:1]
	ds_write_b32 v185, v211 offset:128
	s_or_b64 exec, exec, s[12:13]
	s_waitcnt lgkmcnt(0)
	v_add_u32_e32 v161, v192, v178
	ds_read_b128 v[166:169], v161 offset:224
	ds_read_b128 v[170:173], v161 offset:192
	ds_read_b128 v[212:215], v161 offset:160
	ds_read_b128 v[216:219], v161 offset:128
	s_waitcnt lgkmcnt(3)
	v_pk_mul_f32 v[60:61], v[60:61], v[166:167]
	s_waitcnt lgkmcnt(2)
	v_pk_mul_f32 v[56:57], v[56:57], v[170:171]
	s_waitcnt lgkmcnt(1)
	v_pk_mul_f32 v[52:53], v[52:53], v[212:213]
	v_pk_mul_f32 v[62:63], v[62:63], v[168:169]
	v_pk_mul_f32 v[58:59], v[58:59], v[172:173]
	v_pk_mul_f32 v[54:55], v[54:55], v[214:215]
	s_waitcnt lgkmcnt(0)
	v_pk_mul_f32 v[50:51], v[50:51], v[218:219]
	v_pk_mul_f32 v[48:49], v[48:49], v[216:217]
	v_pk_mul_f32 v[44:45], v[44:45], v[166:167]
	v_pk_mul_f32 v[40:41], v[40:41], v[170:171]
	v_pk_mul_f32 v[36:37], v[36:37], v[212:213]
	v_pk_mul_f32 v[46:47], v[46:47], v[168:169]
	v_pk_mul_f32 v[42:43], v[42:43], v[172:173]
	v_pk_mul_f32 v[38:39], v[38:39], v[214:215]
	v_pk_mul_f32 v[34:35], v[34:35], v[218:219]
	v_pk_mul_f32 v[32:33], v[32:33], v[216:217]
	v_pk_mul_f32 v[28:29], v[28:29], v[166:167]
	v_pk_mul_f32 v[24:25], v[24:25], v[170:171]
	v_pk_mul_f32 v[20:21], v[20:21], v[212:213]
	v_pk_mul_f32 v[30:31], v[30:31], v[168:169]
	v_pk_mul_f32 v[26:27], v[26:27], v[172:173]
	v_pk_mul_f32 v[22:23], v[22:23], v[214:215]
	v_pk_mul_f32 v[18:19], v[18:19], v[218:219]
	v_pk_mul_f32 v[16:17], v[16:17], v[216:217]
	v_pk_mul_f32 v[12:13], v[12:13], v[166:167]
	v_pk_mul_f32 v[8:9], v[8:9], v[170:171]
	v_pk_mul_f32 v[4:5], v[4:5], v[212:213]
	v_pk_mul_f32 v[14:15], v[14:15], v[168:169]
	v_pk_mul_f32 v[10:11], v[10:11], v[172:173]
	v_pk_mul_f32 v[6:7], v[6:7], v[214:215]
	v_pk_mul_f32 v[2:3], v[2:3], v[218:219]
	v_pk_mul_f32 v[0:1], v[0:1], v[216:217]
